# v102 + prep_run rows touch the pooling lines two rows ahead (dummy destinations), loop-top wait in the preamble: re-test of the touch-ahead now that the rope section is shorter
# speedup vs baseline: 1.0084x; 1.0041x over previous
.LBB0_447:
	s_and_b64 vcc, exec, s[0:1]
	s_cbranch_vccz .LBB0_557
	s_movk_i32 s0, 0xff
	v_cmp_lt_i32_e32 vcc, s0, v81
	s_and_saveexec_b64 s[0:1], vcc
	s_xor_b64 s[42:43], exec, s[0:1]
	s_cbranch_execz .LBB0_531
	s_movk_i32 s0, 0x33f
	v_cmp_lt_u32_e32 vcc, s0, v81
	s_and_saveexec_b64 s[0:1], vcc
	s_xor_b64 s[16:17], exec, s[0:1]
	s_cbranch_execz .LBB0_501
	s_movk_i32 s0, 0x7bf
	v_cmp_lt_u32_e32 vcc, s0, v81
	v_readlane_b32 s4, v254, 28
	v_readlane_b32 s0, v255, 7
	v_readlane_b32 s5, v254, 29
	s_add_u32 s2, s4, 0x16f00000
	v_readlane_b32 s1, v255, 8
	s_addc_u32 s3, s5, 0
	s_lshl_b64 s[0:1], s[0:1], 2
	s_add_u32 s0, s4, s0
	s_addc_u32 s1, s5, s1
	s_add_u32 s18, s0, 0x2000
	s_addc_u32 s19, s1, 0
	s_and_saveexec_b64 s[0:1], vcc
	s_xor_b64 s[28:29], exec, s[0:1]
	s_cbranch_execz .LBB0_475
	v_mov_b32_e32 v0, 0xfffff800
	v_mov_b32_e32 v1, -1
	v_mad_u64_u32 v[8:9], s[0:1], v81, 10, v[0:1]
	v_mov_b32_e32 v9, v236
	v_readlane_b32 s4, v255, 11
	v_and_b32_e32 v17, 15, v9
	v_bfe_u32 v19, v9, 4, 2
	v_lshlrev_b32_e32 v21, 2, v17
	v_lshlrev_b32_e32 v12, 6, v19
	v_or_b32_e32 v23, 8, v19
	v_readlane_b32 s5, v255, 12
	v_or_b32_e32 v20, 0x100, v21
	v_min_u32_e32 v0, 9, v23
	v_mov_b64_e32 v[10:11], s[4:5]
	s_movk_i32 s0, 0x1200
	v_or_b32_e32 v22, v12, v21
	v_or_b32_e32 v16, v12, v20
	v_lshlrev_b32_e32 v25, 6, v0
	v_mad_i64_i32 v[10:11], s[0:1], v8, s0, v[10:11]
	v_lshlrev_b32_e32 v160, 1, v22
	v_lshl_add_u64 v[12:13], v[10:11], 0, v[160:161]
	v_lshlrev_b32_e32 v160, 1, v16
	v_or_b32_e32 v24, v25, v21
	v_lshlrev_b32_e32 v4, 4, v17
	v_lshl_add_u64 v[14:15], v[10:11], 0, v[160:161]
	v_lshlrev_b32_e32 v160, 1, v24
	global_load_dwordx4 v[0:3], v4, s[18:19]
	s_nop 0
	global_load_dwordx4 v[4:7], v4, s[18:19] offset:1024
	v_lshl_add_u64 v[10:11], v[10:11], 0, v[160:161]
	global_load_dwordx2 v[46:47], v[12:13], off offset:512
	global_load_dwordx2 v[44:45], v[14:15], off offset:512
	global_load_dwordx2 v[38:39], v[10:11], off offset:512
	v_and_b32_e32 v10, 63, v9
	v_and_b32_e32 v9, 4, v9
	v_cmp_eq_u32_e64 s[36:37], 0, v9
	v_and_b32_e32 v9, 12, v21
	v_cvt_f32_ubyte0_e32 v14, v9
	v_mul_f32_e32 v14, 0xbf549a78, v14
	v_exp_f32_e32 v59, v14
	v_or_b32_e32 v14, 1, v9
	v_cvt_f32_ubyte0_e32 v14, v14
	v_mul_f32_e32 v14, 0xbf549a78, v14
	v_exp_f32_e32 v60, v14
	v_or_b32_e32 v14, 2, v9
	v_or_b32_e32 v9, 3, v9
	v_cvt_f32_ubyte0_e32 v14, v14
	v_cvt_f32_ubyte0_e32 v9, v9
	v_mul_f32_e32 v14, 0xbf549a78, v14
	v_mul_f32_e32 v9, 0xbf549a78, v9
	v_exp_f32_e32 v61, v14
	v_exp_f32_e32 v62, v9
	v_readlane_b32 s0, v254, 28
	v_add_u32_e32 v18, 0x100, v16
	v_or_b32_e32 v20, v25, v20
	v_mov_b32_e32 v64, 0
	v_lshlrev_b32_e32 v160, 3, v10
	v_readlane_b32 s1, v254, 29
	v_cmp_gt_u32_e32 vcc, 10, v23
	v_lshlrev_b32_e64 v58, v19, 1
	v_lshl_add_u64 v[10:11], s[4:5], 0, v[160:161]
	v_cmp_gt_u32_e64 s[38:39], 8, v17
	v_lshl_add_u64 v[12:13], s[2:3], 0, v[160:161]
	v_lshl_add_u64 v[14:15], s[0:1], 0, v[160:161]
	s_mov_b32 s14, 0
	v_lshlrev_b32_e32 v16, 1, v16
	v_lshlrev_b32_e32 v18, 1, v18
	v_lshlrev_b32_e32 v20, 1, v20
	v_lshlrev_b32_e32 v22, 1, v22
	v_lshlrev_b32_e32 v24, 1, v24
	v_mov_b32_e32 v63, v8
	v_mov_b32_e32 v23, 0
	v_mov_b32_e32 v40, 0
	v_mov_b32_e32 v41, v64
	v_mov_b32_e32 v42, 0
	v_mov_b32_e32 v43, v64
	s_waitcnt vmcnt(0)
	s_branch .LBB0_453

.LBB0_475:
	s_andn2_saveexec_b64 s[28:29], s[28:29]
	s_cbranch_execz .LBB0_500
	v_mov_b32_e32 v0, 0xfffff040
	v_mov_b32_e32 v1, -1
	v_mad_u64_u32 v[8:9], s[0:1], v81, 11, v[0:1]
	v_mov_b32_e32 v9, v236
	v_readlane_b32 s4, v255, 11
	v_and_b32_e32 v17, 15, v9
	v_bfe_u32 v19, v9, 4, 2
	v_lshlrev_b32_e32 v21, 2, v17
	v_lshlrev_b32_e32 v12, 6, v19
	v_or_b32_e32 v23, 8, v19
	v_readlane_b32 s5, v255, 12
	v_or_b32_e32 v20, 0x100, v21
	v_min_u32_e32 v0, 9, v23
	v_mov_b64_e32 v[10:11], s[4:5]
	s_movk_i32 s0, 0x1200
	v_or_b32_e32 v22, v12, v21
	v_or_b32_e32 v16, v12, v20
	v_lshlrev_b32_e32 v25, 6, v0
	v_mad_u64_u32 v[10:11], s[0:1], v8, s0, v[10:11]
	v_lshlrev_b32_e32 v160, 1, v22
	v_lshl_add_u64 v[12:13], v[10:11], 0, v[160:161]
	v_lshlrev_b32_e32 v160, 1, v16
	v_or_b32_e32 v24, v25, v21
	v_lshlrev_b32_e32 v4, 4, v17
	v_lshl_add_u64 v[14:15], v[10:11], 0, v[160:161]
	v_lshlrev_b32_e32 v160, 1, v24
	global_load_dwordx4 v[0:3], v4, s[18:19]
	s_nop 0
	global_load_dwordx4 v[4:7], v4, s[18:19] offset:1024
	v_lshl_add_u64 v[10:11], v[10:11], 0, v[160:161]
	global_load_dwordx2 v[46:47], v[12:13], off offset:512
	global_load_dwordx2 v[44:45], v[14:15], off offset:512
	global_load_dwordx2 v[38:39], v[10:11], off offset:512
	v_and_b32_e32 v10, 63, v9
	v_and_b32_e32 v9, 4, v9
	v_cmp_eq_u32_e64 s[36:37], 0, v9
	v_and_b32_e32 v9, 12, v21
	v_cvt_f32_ubyte0_e32 v14, v9
	v_mul_f32_e32 v14, 0xbf549a78, v14
	v_exp_f32_e32 v59, v14
	v_or_b32_e32 v14, 1, v9
	v_cvt_f32_ubyte0_e32 v14, v14
	v_mul_f32_e32 v14, 0xbf549a78, v14
	v_exp_f32_e32 v60, v14
	v_or_b32_e32 v14, 2, v9
	v_or_b32_e32 v9, 3, v9
	v_cvt_f32_ubyte0_e32 v14, v14
	v_cvt_f32_ubyte0_e32 v9, v9
	v_mul_f32_e32 v14, 0xbf549a78, v14
	v_mul_f32_e32 v9, 0xbf549a78, v9
	v_exp_f32_e32 v61, v14
	v_exp_f32_e32 v62, v9
	v_readlane_b32 s0, v254, 28
	v_add_u32_e32 v18, 0x100, v16
	v_or_b32_e32 v20, v25, v20
	v_mov_b32_e32 v64, 0
	v_lshlrev_b32_e32 v160, 3, v10
	v_readlane_b32 s1, v254, 29
	v_cmp_gt_u32_e32 vcc, 10, v23
	v_lshlrev_b32_e64 v58, v19, 1
	v_lshl_add_u64 v[10:11], s[4:5], 0, v[160:161]
	v_cmp_gt_u32_e64 s[38:39], 8, v17
	v_lshl_add_u64 v[12:13], s[2:3], 0, v[160:161]
	v_lshl_add_u64 v[14:15], s[0:1], 0, v[160:161]
	s_mov_b32 s10, 0
	v_lshlrev_b32_e32 v16, 1, v16
	v_lshlrev_b32_e32 v18, 1, v18
	v_lshlrev_b32_e32 v20, 1, v20
	v_lshlrev_b32_e32 v22, 1, v22
	v_lshlrev_b32_e32 v24, 1, v24
	v_mov_b32_e32 v63, v8
	v_mov_b32_e32 v23, 0
	v_mov_b32_e32 v40, 0
	v_mov_b32_e32 v41, v64
	v_mov_b32_e32 v42, 0
	v_mov_b32_e32 v43, v64
	s_waitcnt vmcnt(0)
	s_branch .LBB0_478

.LBB0_501:
	s_andn2_saveexec_b64 s[2:3], s[16:17]
	s_cbranch_execz .LBB0_530
	v_add_u32_e32 v4, 0xffffff00, v81
	s_mov_b32 s0, 0xe38f
	v_mul_u32_u24_sdwa v1, v4, s0 dst_sel:DWORD dst_unused:UNUSED_PAD src0_sel:WORD_0 src1_sel:DWORD
	v_lshrrev_b32_e32 v2, 21, v1
	v_mul_lo_u16_e32 v3, 36, v2
	v_sub_u16_e32 v3, v4, v3
	v_mov_b32_e32 v0, v236
	v_lshrrev_b32_e32 v5, 22, v1
	v_cmp_lt_u16_e32 vcc, 31, v3
	v_lshlrev_b16_e32 v3, 6, v3
	s_and_saveexec_b64 s[0:1], vcc
	s_xor_b64 s[0:1], exec, s[0:1]
	v_lshlrev_b32_e32 v1, 8, v5
	s_movk_i32 s4, 0x3800
	v_add3_u32 v1, v3, v1, s4
	s_andn2_saveexec_b64 s[0:1], s[0:1]
	v_lshl_or_b32 v1, v5, 11, v3
	s_or_b64 exec, exec, s[0:1]
	v_readlane_b32 s8, v254, 28
	v_readlane_b32 s9, v254, 29
	s_movk_i32 s6, 0x1200
	v_lshlrev_b32_e32 v8, 7, v2
	v_mov_b64_e32 v[6:7], s[8:9]
	v_and_b32_e32 v5, 63, v0
	v_mad_u64_u32 v[0:1], s[0:1], v1, s6, v[6:7]
	v_and_b32_e32 v160, 0x80, v8
	v_lshl_add_u64 v[0:1], v[0:1], 0, v[160:161]
	v_lshlrev_b32_e32 v160, 1, v5
	v_lshl_add_u64 v[0:1], v[0:1], 0, v[160:161]
	s_mov_b32 s0, 0xb200000
	v_add_co_u32_e32 v8, vcc, s0, v0
	s_mov_b32 s0, 0xb201000
	s_nop 0
	v_addc_co_u32_e32 v9, vcc, 0, v1, vcc
	v_add_co_u32_e32 v10, vcc, s0, v0
	s_mov_b32 s0, 0xb202000
	s_nop 0
	v_addc_co_u32_e32 v11, vcc, 0, v1, vcc
	v_add_co_u32_e32 v12, vcc, s0, v0
	s_mov_b32 s0, 0xb203000
	s_nop 0
	v_addc_co_u32_e32 v13, vcc, 0, v1, vcc
	v_add_co_u32_e32 v14, vcc, s0, v0
	s_mov_b32 s0, 0xb204000
	s_nop 0
	v_addc_co_u32_e32 v15, vcc, 0, v1, vcc
	v_add_co_u32_e32 v16, vcc, s0, v0
	s_mov_b32 s0, 0xb206000
	s_nop 0
	v_addc_co_u32_e32 v17, vcc, 0, v1, vcc
	v_add_co_u32_e32 v18, vcc, s0, v0
	s_mov_b32 s0, 0xb207000
	s_nop 0
	v_addc_co_u32_e32 v19, vcc, 0, v1, vcc
	v_add_co_u32_e32 v20, vcc, s0, v0
	s_mov_b32 s0, 0xb208000
	s_nop 0
	v_addc_co_u32_e32 v21, vcc, 0, v1, vcc
	v_add_co_u32_e32 v22, vcc, s0, v0
	v_lshl_or_b32 v2, v2, 6, v5
	s_nop 0
	v_addc_co_u32_e32 v23, vcc, 0, v1, vcc
	global_load_ushort v8, v[8:9], off offset:1792
	s_nop 0
	global_load_ushort v9, v[10:11], off offset:2304
	global_load_ushort v24, v[12:13], off offset:2816
	global_load_ushort v25, v[14:15], off offset:3328
	global_load_ushort v26, v[16:17], off offset:3840
	global_load_ushort v27, v[18:19], off offset:256
	global_load_ushort v28, v[20:21], off offset:768
	global_load_ushort v29, v[22:23], off offset:1280
	s_mov_b32 s98, 0xb209700
	s_mov_b32 s99, 0
	v_lshl_add_u64 v[250:251], v[0:1], 0, s[98:99]
	s_movk_i32 s98, 0x1200
	s_nop 0
	global_load_ushort v196, v[250:251], off
	v_lshl_add_u64 v[250:251], v[250:251], 0, s[98:99]
	s_nop 0
	global_load_ushort v197, v[250:251], off
	v_lshl_add_u64 v[250:251], v[250:251], 0, s[98:99]
	s_nop 0
	global_load_ushort v198, v[250:251], off
	v_lshl_add_u64 v[250:251], v[250:251], 0, s[98:99]
	s_nop 0
	global_load_ushort v199, v[250:251], off
	v_lshl_add_u64 v[250:251], v[250:251], 0, s[98:99]
	s_nop 0
	global_load_ushort v200, v[250:251], off
	v_lshl_add_u64 v[250:251], v[250:251], 0, s[98:99]
	s_nop 0
	global_load_ushort v201, v[250:251], off
	v_lshl_add_u64 v[250:251], v[250:251], 0, s[98:99]
	s_nop 0
	global_load_ushort v202, v[250:251], off
	v_lshl_add_u64 v[250:251], v[250:251], 0, s[98:99]
	s_nop 0
	global_load_ushort v203, v[250:251], off
	v_lshl_add_u64 v[250:251], v[250:251], 0, s[98:99]
	s_nop 0
	global_load_ushort v206, v[250:251], off
	v_lshl_add_u64 v[250:251], v[250:251], 0, s[98:99]
	s_nop 0
	global_load_ushort v207, v[250:251], off
	v_lshl_add_u64 v[250:251], v[250:251], 0, s[98:99]
	s_nop 0
	global_load_ushort v208, v[250:251], off
	v_lshl_add_u64 v[250:251], v[250:251], 0, s[98:99]
	s_nop 0
	global_load_ushort v209, v[250:251], off
	v_lshl_add_u64 v[250:251], v[250:251], 0, s[98:99]
	s_nop 0
	global_load_ushort v210, v[250:251], off
	v_lshl_add_u64 v[250:251], v[250:251], 0, s[98:99]
	s_nop 0
	global_load_ushort v211, v[250:251], off
	v_lshl_add_u64 v[250:251], v[250:251], 0, s[98:99]
	s_nop 0
	global_load_ushort v212, v[250:251], off
	v_lshl_add_u64 v[250:251], v[250:251], 0, s[98:99]
	s_nop 0
	global_load_ushort v213, v[250:251], off
	v_lshl_add_u64 v[250:251], v[250:251], 0, s[98:99]
	s_nop 0
	global_load_ushort v214, v[250:251], off
	v_lshl_add_u64 v[250:251], v[250:251], 0, s[98:99]
	s_nop 0
	global_load_ushort v215, v[250:251], off
	v_lshl_add_u64 v[250:251], v[250:251], 0, s[98:99]
	s_nop 0
	global_load_ushort v216, v[250:251], off
	v_lshl_add_u64 v[250:251], v[250:251], 0, s[98:99]
	s_nop 0
	global_load_ushort v217, v[250:251], off
	v_lshl_add_u64 v[250:251], v[250:251], 0, s[98:99]
	s_nop 0
	global_load_ushort v218, v[250:251], off
	v_lshl_add_u64 v[250:251], v[250:251], 0, s[98:99]
	s_nop 0
	global_load_ushort v219, v[250:251], off
	v_lshl_add_u64 v[250:251], v[250:251], 0, s[98:99]
	s_nop 0
	global_load_ushort v220, v[250:251], off
	v_lshl_add_u64 v[250:251], v[250:251], 0, s[98:99]
	s_nop 0
	global_load_ushort v221, v[250:251], off
	v_lshl_add_u64 v[250:251], v[250:251], 0, s[98:99]
	s_nop 0
	global_load_ushort v222, v[250:251], off
	v_lshl_add_u64 v[250:251], v[250:251], 0, s[98:99]
	s_nop 0
	global_load_ushort v223, v[250:251], off
	v_lshl_add_u64 v[250:251], v[250:251], 0, s[98:99]
	s_nop 0
	global_load_ushort v224, v[250:251], off
	v_lshl_add_u64 v[250:251], v[250:251], 0, s[98:99]
	s_nop 0
	global_load_ushort v225, v[250:251], off
	v_lshl_add_u64 v[250:251], v[250:251], 0, s[98:99]
	s_nop 0
	global_load_ushort v226, v[250:251], off
	v_lshl_add_u64 v[250:251], v[250:251], 0, s[98:99]
	s_nop 0
	global_load_ushort v227, v[250:251], off
	v_lshl_add_u64 v[250:251], v[250:251], 0, s[98:99]
	s_nop 0
	global_load_ushort v228, v[250:251], off
	v_lshl_add_u64 v[250:251], v[250:251], 0, s[98:99]
	s_nop 0
	global_load_ushort v229, v[250:251], off
	v_lshl_add_u64 v[250:251], v[250:251], 0, s[98:99]
	s_nop 0
	global_load_ushort v230, v[250:251], off
	v_lshl_add_u64 v[250:251], v[250:251], 0, s[98:99]
	s_nop 0
	global_load_ushort v231, v[250:251], off
	v_lshl_add_u64 v[250:251], v[250:251], 0, s[98:99]
	s_nop 0
	global_load_ushort v232, v[250:251], off
	v_lshl_add_u64 v[250:251], v[250:251], 0, s[98:99]
	s_nop 0
	global_load_ushort v233, v[250:251], off
	v_lshl_add_u64 v[250:251], v[250:251], 0, s[98:99]
	s_nop 0
	global_load_ushort v234, v[250:251], off
	v_lshl_add_u64 v[250:251], v[250:251], 0, s[98:99]
	s_nop 0
	global_load_ushort v235, v[250:251], off
	v_lshl_add_u64 v[250:251], v[250:251], 0, s[98:99]
	s_nop 0
	global_load_ushort v240, v[250:251], off
	v_lshl_add_u64 v[250:251], v[250:251], 0, s[98:99]
	s_nop 0
	global_load_ushort v241, v[250:251], off
	v_lshl_add_u64 v[250:251], v[250:251], 0, s[98:99]
	s_nop 0
	global_load_ushort v242, v[250:251], off
	v_lshl_add_u64 v[250:251], v[250:251], 0, s[98:99]
	s_nop 0
	global_load_ushort v243, v[250:251], off
	v_lshl_add_u64 v[250:251], v[250:251], 0, s[98:99]
	s_nop 0
	global_load_ushort v248, v[250:251], off
	v_lshl_add_u64 v[250:251], v[250:251], 0, s[98:99]
	s_nop 0
	global_load_ushort v249, v[250:251], off
	v_lshl_add_u64 v[250:251], v[250:251], 0, s[98:99]
	v_mad_u64_u32 v[6:7], s[0:1], v2, s6, v[6:7]
	s_mov_b32 s0, 0xb209000
	s_nop 0
	v_add_co_u32_e32 v10, vcc, s0, v0
	s_mov_b32 s0, 0xb20a000
	s_nop 0
	v_addc_co_u32_e32 v11, vcc, 0, v1, vcc
	v_add_co_u32_e32 v12, vcc, s0, v0
	s_mov_b32 s0, 0xb20b000
	s_nop 0
	v_addc_co_u32_e32 v13, vcc, 0, v1, vcc
	v_add_co_u32_e32 v14, vcc, s0, v0
	s_mov_b32 s0, 0xb20c000
	s_nop 0
	v_addc_co_u32_e32 v15, vcc, 0, v1, vcc
	v_add_co_u32_e32 v16, vcc, s0, v0
	s_mov_b32 s0, 0xb20d000
	s_nop 0
	v_addc_co_u32_e32 v17, vcc, 0, v1, vcc
	v_add_co_u32_e32 v18, vcc, s0, v0
	s_mov_b32 s0, 0xb20f000
	s_nop 0
	v_addc_co_u32_e32 v19, vcc, 0, v1, vcc
	v_lshlrev_b32_e32 v160, 1, v3
	v_add_co_u32_e32 v20, vcc, s0, v0
	v_lshl_add_u64 v[2:3], v[6:7], 0, v[160:161]
	s_nop 0
	v_addc_co_u32_e32 v21, vcc, 0, v1, vcc
	s_mov_b32 s0, 0x19300000
	v_add_co_u32_e32 v22, vcc, s0, v2
	s_mov_b32 s0, 0xb210000
	s_nop 0
	v_addc_co_u32_e32 v23, vcc, 0, v3, vcc
	v_readlane_b32 s10, v255, 11
	v_readlane_b32 s11, v255, 12
	v_mov_b32_e32 v60, 0
	s_mov_b32 s14, 0
	v_mov_b32_e32 v38, 0
	v_mov_b32_e32 v39, v60
	v_mov_b32_e32 v36, 0
	v_mov_b32_e32 v37, v60
	s_waitcnt vmcnt(0)
	v_lshl_or_b32 v6, v9, 16, v8
	v_lshl_or_b32 v7, v25, 16, v24
	v_lshl_or_b32 v8, v27, 16, v26
	v_lshl_or_b32 v9, v29, 16, v28
	global_store_dwordx4 v[22:23], v[6:9], off
	s_nop 1
	v_add_co_u32_e32 v6, vcc, s0, v0
	s_mov_b32 s0, 0xb211000
	s_nop 0
	v_addc_co_u32_e32 v7, vcc, 0, v1, vcc
	v_add_co_u32_e32 v8, vcc, s0, v0
	s_mov_b32 s0, 0xb212000
	s_nop 0
	v_addc_co_u32_e32 v9, vcc, 0, v1, vcc
	global_load_ushort v5, v[10:11], off offset:1792
	global_load_ushort v26, v[12:13], off offset:2304
	global_load_ushort v27, v[14:15], off offset:2816
	global_load_ushort v28, v[16:17], off offset:3328
	global_load_ushort v29, v[18:19], off offset:3840
	global_load_ushort v30, v[20:21], off offset:256
	global_load_ushort v31, v[6:7], off offset:768
	s_nop 0
	global_load_ushort v9, v[8:9], off offset:1280
	v_add_co_u32_e32 v10, vcc, s0, v0
	s_mov_b32 s0, 0xb213000
	s_nop 0
	v_addc_co_u32_e32 v11, vcc, 0, v1, vcc
	v_add_co_u32_e32 v12, vcc, s0, v0
	s_mov_b32 s0, 0xb214000
	s_nop 0
	v_addc_co_u32_e32 v13, vcc, 0, v1, vcc
	v_add_co_u32_e32 v14, vcc, s0, v0
	s_mov_b32 s0, 0xb215000
	s_nop 0
	v_addc_co_u32_e32 v15, vcc, 0, v1, vcc
	v_add_co_u32_e32 v16, vcc, s0, v0
	s_mov_b32 s0, 0xb216000
	s_nop 0
	v_addc_co_u32_e32 v17, vcc, 0, v1, vcc
	v_add_co_u32_e32 v18, vcc, s0, v0
	s_mov_b32 s0, 0xb218000
	s_nop 0
	v_addc_co_u32_e32 v19, vcc, 0, v1, vcc
	v_add_co_u32_e32 v20, vcc, s0, v0
	s_mov_b32 s0, 0xb219000
	s_nop 0
	v_addc_co_u32_e32 v21, vcc, 0, v1, vcc
	v_add_co_u32_e32 v22, vcc, s0, v0
	s_mov_b32 s0, 0xb21a000
	s_nop 0
	v_addc_co_u32_e32 v23, vcc, 0, v1, vcc
	v_add_co_u32_e32 v24, vcc, s0, v0
	s_mov_b64 s[0:1], 0x19300000
	v_lshl_add_u64 v[2:3], v[2:3], 0, s[0:1]
	v_addc_co_u32_e32 v25, vcc, 0, v1, vcc
	s_mov_b32 s0, 0xb21b000
	s_waitcnt vmcnt(0)
	v_lshl_or_b32 v6, v26, 16, v5
	v_lshl_or_b32 v7, v28, 16, v27
	v_lshl_or_b32 v8, v30, 16, v29
	v_lshl_or_b32 v9, v9, 16, v31
	global_store_dwordx4 v[2:3], v[6:9], off offset:16
	global_load_ushort v5, v[10:11], off offset:1792
	s_nop 0
	global_load_ushort v6, v[12:13], off offset:2304
	global_load_ushort v7, v[14:15], off offset:2816
	global_load_ushort v8, v[16:17], off offset:3328
	global_load_ushort v9, v[18:19], off offset:3840
	global_load_ushort v26, v[20:21], off offset:256
	global_load_ushort v27, v[22:23], off offset:768
	global_load_ushort v28, v[24:25], off offset:1280
	v_add_co_u32_e32 v10, vcc, s0, v0
	s_mov_b32 s0, 0xb21c000
	s_nop 0
	v_addc_co_u32_e32 v11, vcc, 0, v1, vcc
	v_add_co_u32_e32 v12, vcc, s0, v0
	s_mov_b32 s0, 0xb21d000
	s_nop 0
	v_addc_co_u32_e32 v13, vcc, 0, v1, vcc
	v_add_co_u32_e32 v14, vcc, s0, v0
	s_mov_b32 s0, 0xb21e000
	s_nop 0
	v_addc_co_u32_e32 v15, vcc, 0, v1, vcc
	v_add_co_u32_e32 v16, vcc, s0, v0
	s_mov_b32 s0, 0xb21f000
	s_nop 0
	v_addc_co_u32_e32 v17, vcc, 0, v1, vcc
	v_add_co_u32_e32 v18, vcc, s0, v0
	s_mov_b32 s0, 0xb221000
	s_nop 0
	v_addc_co_u32_e32 v19, vcc, 0, v1, vcc
	v_add_co_u32_e32 v20, vcc, s0, v0
	s_mov_b32 s0, 0xb222000
	s_nop 0
	v_addc_co_u32_e32 v21, vcc, 0, v1, vcc
	v_add_co_u32_e32 v22, vcc, s0, v0
	s_mov_b32 s0, 0xb223000
	s_nop 0
	v_addc_co_u32_e32 v23, vcc, 0, v1, vcc
	v_add_co_u32_e32 v24, vcc, s0, v0
	s_mov_b32 s0, 0xb224000
	s_nop 0
	v_addc_co_u32_e32 v25, vcc, 0, v1, vcc
	s_waitcnt vmcnt(0)
	v_lshl_or_b32 v6, v6, 16, v5
	v_lshl_or_b32 v7, v8, 16, v7
	v_lshl_or_b32 v8, v26, 16, v9
	v_lshl_or_b32 v9, v28, 16, v27
	global_store_dwordx4 v[2:3], v[6:9], off offset:32
	global_load_ushort v5, v[10:11], off offset:1792
	s_nop 0
	global_load_ushort v6, v[12:13], off offset:2304
	global_load_ushort v7, v[14:15], off offset:2816
	global_load_ushort v8, v[16:17], off offset:3328
	global_load_ushort v9, v[18:19], off offset:3840
	global_load_ushort v26, v[20:21], off offset:256
	global_load_ushort v27, v[22:23], off offset:768
	global_load_ushort v28, v[24:25], off offset:1280
	v_add_co_u32_e32 v10, vcc, s0, v0
	s_mov_b32 s0, 0xb225000
	s_nop 0
	v_addc_co_u32_e32 v11, vcc, 0, v1, vcc
	v_add_co_u32_e32 v12, vcc, s0, v0
	s_mov_b32 s0, 0xb226000
	s_nop 0
	v_addc_co_u32_e32 v13, vcc, 0, v1, vcc
	v_add_co_u32_e32 v14, vcc, s0, v0
	s_mov_b32 s0, 0xb227000
	s_nop 0
	v_addc_co_u32_e32 v15, vcc, 0, v1, vcc
	v_add_co_u32_e32 v16, vcc, s0, v0
	s_mov_b32 s0, 0xb228000
	s_nop 0
	v_addc_co_u32_e32 v17, vcc, 0, v1, vcc
	v_add_co_u32_e32 v18, vcc, s0, v0
	s_mov_b32 s0, 0xb22a000
	s_nop 0
	v_addc_co_u32_e32 v19, vcc, 0, v1, vcc
	v_add_co_u32_e32 v20, vcc, s0, v0
	s_mov_b32 s0, 0xb22b000
	s_nop 0
	v_addc_co_u32_e32 v21, vcc, 0, v1, vcc
	v_add_co_u32_e32 v22, vcc, s0, v0
	s_mov_b32 s0, 0xb22c000
	s_nop 0
	v_addc_co_u32_e32 v23, vcc, 0, v1, vcc
	v_add_co_u32_e32 v24, vcc, s0, v0
	s_mov_b32 s0, 0xb22d000
	s_nop 0
	v_addc_co_u32_e32 v25, vcc, 0, v1, vcc
	s_waitcnt vmcnt(0)
	v_lshl_or_b32 v6, v6, 16, v5
	v_lshl_or_b32 v7, v8, 16, v7
	v_lshl_or_b32 v8, v26, 16, v9
	v_lshl_or_b32 v9, v28, 16, v27
	global_store_dwordx4 v[2:3], v[6:9], off offset:48
	global_load_ushort v5, v[10:11], off offset:1792
	s_nop 0
	global_load_ushort v6, v[12:13], off offset:2304
	global_load_ushort v7, v[14:15], off offset:2816
	global_load_ushort v8, v[16:17], off offset:3328
	global_load_ushort v9, v[18:19], off offset:3840
	global_load_ushort v26, v[20:21], off offset:256
	global_load_ushort v27, v[22:23], off offset:768
	global_load_ushort v28, v[24:25], off offset:1280
	v_add_co_u32_e32 v10, vcc, s0, v0
	s_mov_b32 s0, 0xb22e000
	s_nop 0
	v_addc_co_u32_e32 v11, vcc, 0, v1, vcc
	v_add_co_u32_e32 v12, vcc, s0, v0
	s_mov_b32 s0, 0xb22f000
	s_nop 0
	v_addc_co_u32_e32 v13, vcc, 0, v1, vcc
	v_add_co_u32_e32 v14, vcc, s0, v0
	s_mov_b32 s0, 0xb230000
	s_nop 0
	v_addc_co_u32_e32 v15, vcc, 0, v1, vcc
	v_add_co_u32_e32 v16, vcc, s0, v0
	s_mov_b32 s0, 0xb231000
	s_nop 0
	v_addc_co_u32_e32 v17, vcc, 0, v1, vcc
	v_add_co_u32_e32 v18, vcc, s0, v0
	s_mov_b32 s0, 0xb233000
	s_nop 0
	v_addc_co_u32_e32 v19, vcc, 0, v1, vcc
	v_add_co_u32_e32 v20, vcc, s0, v0
	s_mov_b32 s0, 0xb234000
	s_nop 0
	v_addc_co_u32_e32 v21, vcc, 0, v1, vcc
	v_add_co_u32_e32 v22, vcc, s0, v0
	s_mov_b32 s0, 0xb235000
	s_nop 0
	v_addc_co_u32_e32 v23, vcc, 0, v1, vcc
	v_add_co_u32_e32 v24, vcc, s0, v0
	s_mov_b32 s0, 0xb236000
	s_nop 0
	v_addc_co_u32_e32 v25, vcc, 0, v1, vcc
	s_waitcnt vmcnt(0)
	v_lshl_or_b32 v6, v6, 16, v5
	v_lshl_or_b32 v7, v8, 16, v7
	v_lshl_or_b32 v8, v26, 16, v9
	v_lshl_or_b32 v9, v28, 16, v27
	global_store_dwordx4 v[2:3], v[6:9], off offset:64
	global_load_ushort v5, v[10:11], off offset:1792
	s_nop 0
	global_load_ushort v6, v[12:13], off offset:2304
	global_load_ushort v7, v[14:15], off offset:2816
	global_load_ushort v8, v[16:17], off offset:3328
	global_load_ushort v9, v[18:19], off offset:3840
	global_load_ushort v26, v[20:21], off offset:256
	global_load_ushort v27, v[22:23], off offset:768
	global_load_ushort v28, v[24:25], off offset:1280
	v_add_co_u32_e32 v10, vcc, s0, v0
	s_mov_b32 s0, 0xb237000
	s_nop 0
	v_addc_co_u32_e32 v11, vcc, 0, v1, vcc
	v_add_co_u32_e32 v12, vcc, s0, v0
	s_mov_b32 s0, 0xb238000
	s_nop 0
	v_addc_co_u32_e32 v13, vcc, 0, v1, vcc
	v_add_co_u32_e32 v14, vcc, s0, v0
	s_mov_b32 s0, 0xb239000
	s_nop 0
	v_addc_co_u32_e32 v15, vcc, 0, v1, vcc
	v_add_co_u32_e32 v16, vcc, s0, v0
	s_mov_b32 s0, 0xb23a000
	s_nop 0
	v_addc_co_u32_e32 v17, vcc, 0, v1, vcc
	v_add_co_u32_e32 v18, vcc, s0, v0
	s_mov_b32 s0, 0xb23c000
	s_nop 0
	v_addc_co_u32_e32 v19, vcc, 0, v1, vcc
	v_add_co_u32_e32 v20, vcc, s0, v0
	s_mov_b32 s0, 0xb23d000
	s_nop 0
	v_addc_co_u32_e32 v21, vcc, 0, v1, vcc
	v_add_co_u32_e32 v22, vcc, s0, v0
	s_mov_b32 s0, 0xb23e000
	s_nop 0
	v_addc_co_u32_e32 v23, vcc, 0, v1, vcc
	v_add_co_u32_e32 v24, vcc, s0, v0
	s_mov_b32 s0, 0xb23f000
	s_nop 0
	v_addc_co_u32_e32 v25, vcc, 0, v1, vcc
	s_waitcnt vmcnt(0)
	v_lshl_or_b32 v6, v6, 16, v5
	v_lshl_or_b32 v7, v8, 16, v7
	v_lshl_or_b32 v8, v26, 16, v9
	v_lshl_or_b32 v9, v28, 16, v27
	global_store_dwordx4 v[2:3], v[6:9], off offset:80
	global_load_ushort v5, v[10:11], off offset:1792
	s_nop 0
	global_load_ushort v6, v[12:13], off offset:2304
	global_load_ushort v7, v[14:15], off offset:2816
	global_load_ushort v8, v[16:17], off offset:3328
	global_load_ushort v9, v[18:19], off offset:3840
	global_load_ushort v26, v[20:21], off offset:256
	global_load_ushort v27, v[22:23], off offset:768
	s_nop 0
	global_load_ushort v24, v[24:25], off offset:1280
	v_add_co_u32_e32 v10, vcc, s0, v0
	s_mov_b32 s0, 0xb240000
	s_nop 0
	v_addc_co_u32_e32 v11, vcc, 0, v1, vcc
	v_add_co_u32_e32 v12, vcc, s0, v0
	s_mov_b32 s0, 0xb241000
	s_nop 0
	v_addc_co_u32_e32 v13, vcc, 0, v1, vcc
	v_add_co_u32_e32 v14, vcc, s0, v0
	s_mov_b32 s0, 0xb242000
	s_nop 0
	v_addc_co_u32_e32 v15, vcc, 0, v1, vcc
	v_add_co_u32_e32 v16, vcc, s0, v0
	s_mov_b32 s0, 0xb243000
	s_nop 0
	v_addc_co_u32_e32 v17, vcc, 0, v1, vcc
	v_add_co_u32_e32 v18, vcc, s0, v0
	s_mov_b32 s0, 0xb245000
	s_nop 0
	v_addc_co_u32_e32 v19, vcc, 0, v1, vcc
	v_add_co_u32_e32 v20, vcc, s0, v0
	s_mov_b32 s0, 0xb246000
	s_nop 0
	v_addc_co_u32_e32 v21, vcc, 0, v1, vcc
	v_add_co_u32_e32 v22, vcc, s0, v0
	s_mov_b32 s0, 0xb247000
	s_nop 0
	v_addc_co_u32_e32 v23, vcc, 0, v1, vcc
	v_add_co_u32_e32 v0, vcc, s0, v0
	v_readlane_b32 s0, v255, 7
	s_nop 0
	v_addc_co_u32_e32 v1, vcc, 0, v1, vcc
	v_readlane_b32 s1, v255, 8
	s_lshl_b64 s[0:1], s[0:1], 2
	s_add_u32 s0, s8, s0
	s_addc_u32 s1, s9, s1
	s_waitcnt vmcnt(0)
	v_lshl_or_b32 v6, v6, 16, v5
	v_lshl_or_b32 v7, v8, 16, v7
	v_lshl_or_b32 v8, v26, 16, v9
	v_lshl_or_b32 v9, v24, 16, v27
	global_store_dwordx4 v[2:3], v[6:9], off offset:96
	global_load_ushort v5, v[10:11], off offset:1792
	s_nop 0
	global_load_ushort v6, v[12:13], off offset:2304
	global_load_ushort v7, v[14:15], off offset:2816
	global_load_ushort v10, v[16:17], off offset:3328
	global_load_ushort v11, v[18:19], off offset:3840
	s_nop 0
	global_load_ushort v12, v[20:21], off offset:256
	global_load_ushort v13, v[22:23], off offset:768
	global_load_ushort v14, v[0:1], off offset:1280
	v_mov_b32_e32 v0, 0x200
	v_lshl_add_u32 v54, v4, 3, v0
	v_mov_b32_e32 v15, v236
	v_mov_b64_e32 v[0:1], s[10:11]
	v_mad_u64_u32 v[8:9], s[4:5], v54, s6, v[0:1]
	s_waitcnt vmcnt(0)
	v_lshl_or_b32 v4, v6, 16, v5
	v_lshl_or_b32 v5, v10, 16, v7
	v_lshl_or_b32 v6, v12, 16, v11
	v_lshl_or_b32 v7, v14, 16, v13
	global_store_dwordx4 v[2:3], v[4:7], off offset:112
	s_nop 0
	v_and_b32_e32 v14, 15, v15
	v_bfe_u32 v17, v15, 4, 2
	v_lshlrev_b32_e32 v19, 2, v14
	v_lshlrev_b32_e32 v2, 6, v17
	v_or_b32_e32 v21, 8, v17
	v_lshlrev_b32_e32 v160, 4, v14
	v_or_b32_e32 v23, 0x100, v19
	v_min_u32_e32 v3, 9, v21
	v_or_b32_e32 v20, v2, v19
	v_lshl_add_u64 v[0:1], s[0:1], 0, v[160:161]
	v_or_b32_e32 v16, v2, v23
	v_lshlrev_b32_e32 v24, 6, v3
	s_mov_b64 s[0:1], 0x2000
	v_lshlrev_b32_e32 v160, 1, v20
	v_lshl_add_u64 v[4:5], v[0:1], 0, s[0:1]
	v_add_co_u32_e32 v0, vcc, s20, v0
	v_lshl_add_u64 v[10:11], v[8:9], 0, v[160:161]
	v_lshlrev_b32_e32 v160, 1, v16
	v_or_b32_e32 v22, v24, v19
	v_addc_co_u32_e32 v1, vcc, 0, v1, vcc
	v_lshl_add_u64 v[12:13], v[8:9], 0, v[160:161]
	v_lshlrev_b32_e32 v160, 1, v22
	global_load_dwordx4 v[0:3], v[0:1], off
	s_nop 0
	global_load_dwordx4 v[4:7], v[4:5], off offset:1024
	v_lshl_add_u64 v[8:9], v[8:9], 0, v[160:161]
	global_load_dwordx2 v[42:43], v[10:11], off offset:512
	global_load_dwordx2 v[40:41], v[12:13], off offset:512
	global_load_dwordx2 v[34:35], v[8:9], off offset:512
	v_and_b32_e32 v8, 63, v15
	v_and_b32_e32 v9, 4, v15
	v_lshlrev_b32_e32 v160, 3, v8
	v_cmp_eq_u32_e64 s[36:37], 0, v9
	v_cmp_gt_u32_e64 s[38:39], 8, v14
	v_and_b32_e32 v14, 12, v19
	v_lshl_add_u64 v[8:9], s[8:9], 0, v[160:161]
	s_mov_b64 s[0:1], 0x16f00000
	v_lshl_add_u64 v[12:13], v[8:9], 0, s[0:1]
	v_cvt_f32_ubyte0_e32 v8, v14
	v_mul_f32_e32 v8, 0xbf549a78, v8
	v_exp_f32_e32 v56, v8
	v_or_b32_e32 v8, 1, v14
	v_cvt_f32_ubyte0_e32 v8, v8
	v_mul_f32_e32 v8, 0xbf549a78, v8
	v_exp_f32_e32 v57, v8
	v_or_b32_e32 v8, 2, v14
	v_cvt_f32_ubyte0_e32 v8, v8
	v_mul_f32_e32 v8, 0xbf549a78, v8
	v_exp_f32_e32 v58, v8
	v_or_b32_e32 v8, 3, v14
	v_cvt_f32_ubyte0_e32 v8, v8
	v_mul_f32_e32 v8, 0xbf549a78, v8
	v_exp_f32_e32 v59, v8
	v_mad_i64_i32 v[8:9], s[0:1], v54, s6, 0
	v_add_u32_e32 v18, 0x100, v16
	v_or_b32_e32 v24, v24, v23
	v_or_b32_e32 v8, v8, v160
	v_cmp_gt_u32_e32 vcc, 10, v21
	v_lshlrev_b32_e64 v55, v17, 1
	v_lshl_add_u64 v[10:11], s[10:11], 0, v[160:161]
	v_lshl_add_u64 v[14:15], s[10:11], 0, v[8:9]
	v_lshlrev_b32_e32 v8, 1, v16
	v_lshlrev_b32_e32 v16, 1, v18
	v_lshlrev_b32_e32 v18, 1, v24
	v_lshlrev_b32_e32 v20, 1, v20
	v_lshlrev_b32_e32 v22, 1, v22
	v_mov_b32_e32 v21, 0
	s_waitcnt vmcnt(0)
	s_branch .LBB0_508

.LBB0_531:
	s_andn2_saveexec_b64 s[2:3], s[42:43]
	s_cbranch_execz .LBB0_556
	v_readlane_b32 s0, v255, 7
	v_mov_b32_e32 v9, v236
	v_readlane_b32 s1, v255, 8
	s_lshl_b64 s[0:1], s[0:1], 2
	v_bfe_u32 v19, v9, 4, 2
	v_readlane_b32 s4, v254, 28
	v_and_b32_e32 v17, 15, v9
	v_or_b32_e32 v23, 8, v19
	v_readlane_b32 s5, v254, 29
	s_add_u32 s0, s4, s0
	v_min_u32_e32 v0, 9, v23
	s_addc_u32 s1, s5, s1
	v_lshlrev_b32_e32 v160, 4, v17
	v_readlane_b32 s6, v255, 11
	v_lshlrev_b32_e32 v21, 2, v17
	v_lshlrev_b32_e32 v12, 6, v19
	v_lshlrev_b32_e32 v24, 6, v0
	v_lshl_add_u64 v[0:1], s[0:1], 0, v[160:161]
	s_mov_b64 s[0:1], 0x2000
	v_readlane_b32 s7, v255, 12
	v_lshlrev_b32_e32 v56, 1, v81
	v_or_b32_e32 v18, 0x100, v21
	v_lshl_add_u64 v[4:5], v[0:1], 0, s[0:1]
	v_mov_b64_e32 v[10:11], s[6:7]
	s_movk_i32 s0, 0x1200
	v_or_b32_e32 v20, v12, v21
	v_or_b32_e32 v8, v12, v18
	v_mad_i64_i32 v[10:11], s[0:1], v56, s0, v[10:11]
	v_lshlrev_b32_e32 v160, 1, v20
	v_add_co_u32_e32 v0, vcc, s20, v0
	v_lshl_add_u64 v[12:13], v[10:11], 0, v[160:161]
	v_lshlrev_b32_e32 v160, 1, v8
	v_or_b32_e32 v22, v24, v21
	v_addc_co_u32_e32 v1, vcc, 0, v1, vcc
	v_lshl_add_u64 v[14:15], v[10:11], 0, v[160:161]
	v_lshlrev_b32_e32 v160, 1, v22
	global_load_dwordx4 v[0:3], v[0:1], off
	s_nop 0
	global_load_dwordx4 v[4:7], v[4:5], off offset:1024
	v_lshl_add_u64 v[10:11], v[10:11], 0, v[160:161]
	global_load_dwordx2 v[44:45], v[12:13], off offset:512
	global_load_dwordx2 v[42:43], v[14:15], off offset:512
	global_load_dwordx2 v[36:37], v[10:11], off offset:512
	v_and_b32_e32 v10, 63, v9
	v_and_b32_e32 v9, 4, v9
	v_cmp_eq_u32_e64 s[36:37], 0, v9
	v_and_b32_e32 v9, 12, v21
	v_cmp_gt_u32_e64 s[38:39], 8, v17
	v_cvt_f32_ubyte0_e32 v17, v9
	v_mul_f32_e32 v17, 0xbf549a78, v17
	v_exp_f32_e32 v58, v17
	v_or_b32_e32 v17, 1, v9
	v_cvt_f32_ubyte0_e32 v17, v17
	v_mul_f32_e32 v17, 0xbf549a78, v17
	v_exp_f32_e32 v59, v17
	v_or_b32_e32 v17, 2, v9
	v_or_b32_e32 v9, 3, v9
	v_cvt_f32_ubyte0_e32 v17, v17
	v_cvt_f32_ubyte0_e32 v9, v9
	v_mul_f32_e32 v17, 0xbf549a78, v17
	v_mul_f32_e32 v9, 0xbf549a78, v9
	v_exp_f32_e32 v60, v17
	v_exp_f32_e32 v61, v9
	v_lshlrev_b32_e32 v160, 3, v10
	v_add_u32_e32 v16, 0x100, v8
	v_or_b32_e32 v18, v24, v18
	v_mov_b32_e32 v63, 0
	v_lshl_add_u64 v[12:13], s[4:5], 0, v[160:161]
	s_mov_b64 s[0:1], 0x16f00000
	v_cmp_gt_u32_e32 vcc, 10, v23
	v_lshlrev_b32_e64 v57, v19, 1
	v_lshl_add_u64 v[10:11], s[6:7], 0, v[160:161]
	v_lshl_add_u64 v[14:15], v[12:13], 0, s[0:1]
	s_mov_b32 s14, 0
	v_lshlrev_b32_e32 v8, 1, v8
	v_lshlrev_b32_e32 v16, 1, v16
	v_lshlrev_b32_e32 v18, 1, v18
	v_lshlrev_b32_e32 v20, 1, v20
	v_lshlrev_b32_e32 v22, 1, v22
	v_mov_b32_e32 v62, v56
	v_mov_b32_e32 v21, 0
	v_mov_b32_e32 v38, 0
	v_mov_b32_e32 v39, v63
	v_mov_b32_e32 v40, 0
	v_mov_b32_e32 v41, v63
	s_waitcnt vmcnt(0)
	s_branch .LBB0_534
.LBB0_533:
	s_or_b64 exec, exec, s[0:1]
	v_sub_u32_e32 v9, v17, v63
	v_cvt_f32_i32_e32 v9, v9
	s_waitcnt vmcnt(2)
	v_lshlrev_b32_e32 v200, 16, v196
	v_and_b32_e32 v201, 0xffff0000, v196
	v_lshlrev_b32_e32 v202, 16, v198
	v_and_b32_e32 v203, 0xffff0000, v198
	v_pk_add_f32 v[200:201], v[200:201], v[202:203] neg_lo:[0,1] neg_hi:[0,1]
	v_lshlrev_b32_e32 v198, 16, v199
	v_pk_add_f32 v[40:41], v[40:41], v[200:201]
	v_lshlrev_b32_e32 v200, 16, v197
	v_and_b32_e32 v201, 0xffff0000, v197
	v_and_b32_e32 v199, 0xffff0000, v199
	v_pk_add_f32 v[200:201], v[200:201], v[198:199] neg_lo:[0,1] neg_hi:[0,1]
	s_nop 0
	v_pk_add_f32 v[38:39], v[38:39], v[200:201]
	v_bfe_u32 v222, v236, 4, 2
	v_lshlrev_b32_e64 v222, v222, 1
	v_add_u32_e32 v222, -1, v222
	v_mul_u32_u24_e32 v208, 0x1200, v222
	v_mov_b32_e32 v209, 0
	v_lshl_add_u64 v[212:213], v[206:207], 0, v[208:209]
	s_nop 1
	global_load_dwordx2 v[216:217], v[206:207], off
	global_load_dwordx2 v[218:219], v[212:213], off
	v_lshlrev_b32_e32 v36, 16, v34
	v_and_b32_e32 v37, 0xffff0000, v34
	s_add_i32 s14, s14, 1
	v_rcp_iflag_f32_e32 v32, v9
	v_lshlrev_b64 v[24:25], 11, v[24:25]
	v_lshl_add_u64 v[24:25], v[14:15], 0, v[24:25]
	v_add_u32_e32 v62, 1, v62
	v_pk_fma_f32 v[36:37], v[32:33], v[40:41], v[36:37] op_sel_hi:[0,1,1] neg_lo:[0,0,1] neg_hi:[0,0,1]
	v_cvt_pk_bf16_f32 v34, v36, v37
	v_lshlrev_b32_e32 v36, 16, v35
	v_and_b32_e32 v37, 0xffff0000, v35
	v_pk_fma_f32 v[32:33], v[32:33], v[38:39], v[36:37] op_sel_hi:[0,1,1] neg_lo:[0,0,1] neg_hi:[0,0,1]
	v_cvt_pk_bf16_f32 v35, v32, v33
	s_cmp_eq_u32 s14, 2
	v_mov_b32_e32 v21, v17
	v_mov_b32_e32 v44, v26
	v_mov_b32_e32 v45, v27
	v_mov_b32_e32 v42, v28
	v_mov_b32_e32 v43, v29
	v_mov_b32_e32 v36, v30
	v_mov_b32_e32 v37, v31
	global_store_dwordx2 v[24:25], v[34:35], off
	s_cbranch_scc1 .LBB0_556
.LBB0_534:
	v_readlane_b32 s0, v255, 11
	v_readlane_b32 s1, v255, 12
	v_add_u32_e32 v24, s14, v56
	s_cmp_gt_u32 s14, 0
	v_mov_b64_e32 v[26:27], s[0:1]
	s_movk_i32 s0, 0x1200
	v_mad_i64_i32 v[32:33], s[0:1], v24, s0, v[26:27]
	v_mov_b32_e32 v26, v44
	v_mov_b32_e32 v27, v45
	v_mov_b32_e32 v28, v42
	v_mov_b32_e32 v29, v43
	v_mov_b32_e32 v30, v36
	v_mov_b32_e32 v31, v37
	s_cbranch_scc1 .LBB0_536
	v_lshl_add_u64 v[26:27], v[32:33], 0, s[34:35]
	v_mov_b32_e32 v9, v161
	v_mov_b32_e32 v17, v161
	v_lshl_add_u64 v[28:29], v[26:27], 0, v[8:9]
	v_lshl_add_u64 v[30:31], v[26:27], 0, v[16:17]
	v_mov_b32_e32 v19, v161
	v_lshl_add_u64 v[34:35], v[26:27], 0, v[18:19]
	global_load_dwordx2 v[26:27], v[28:29], off
	s_nop 0
	global_load_dwordx2 v[28:29], v[30:31], off
	s_nop 0
	global_load_dwordx2 v[30:31], v[34:35], off
